# P0 w_in transpose items: 8 dwordx4 weight loads + 8 gain loads per item instead of 32+32 dword loads
# baseline (speedup 1.0000x reference)
.LBB0_71:
	s_andn2_saveexec_b64 s[2:3], s[2:3]
	v_lshrrev_b32_e32 v18, 1, v18
	v_and_b32_e32 v18, 28, v18
	v_or_b32_e32 v19, v18, v22
	v_add_u32_e32 v18, v97, v18
	v_and_b32_e32 v17, 0xffffffc0, v17
	v_cndmask_b32_e64 v18, v18, v19, s[4:5]
	v_add_u32_e32 v18, v18, v17
	s_or_b64 exec, exec, s[2:3]
	v_lshlrev_b32_e32 v16, 6, v16
	v_and_b32_e32 v100, 63, v214
	v_and_b32_e32 v101, 7, v100
	v_lshlrev_b32_e32 v103, 4, v101
	ds_bpermute_b32 v18, v103, v18
	v_lshrrev_b32_e32 v102, 3, v100
	v_ashrrev_i32_e32 v17, 31, v16
	v_add_u32_e32 v104, v16, v102
	v_ashrrev_i32_e32 v105, 31, v104
	v_lshl_add_u64 v[106:107], v[104:105], 2, s[38:39]
	global_load_dword v126, v[106:107], off
	global_load_dword v127, v[106:107], off offset:32
	global_load_dword v128, v[106:107], off offset:64
	global_load_dword v129, v[106:107], off offset:96
	global_load_dword v130, v[106:107], off offset:128
	global_load_dword v131, v[106:107], off offset:160
	global_load_dword v132, v[106:107], off offset:192
	global_load_dword v133, v[106:107], off offset:224
	v_lshrrev_b32_e32 v108, 5, v100
	v_mul_u32_u24_e32 v108, 33, v108
	v_and_b32_e32 v109, 31, v100
	v_add_u32_e32 v108, v108, v109
	v_mul_u32_u24_e32 v109, 33, v102
	v_lshl_add_u32 v109, v101, 2, v109
	v_sub_u32_e32 v108, v109, v108
	v_lshl_add_u32 v108, v108, 2, v26
	s_waitcnt lgkmcnt(0)
	v_ashrrev_i32_e32 v19, 31, v18
	v_lshl_add_u64 v[18:19], v[18:19], 2, s[40:41]
	v_add_u32_e32 v109, 0, v104
	v_mad_i64_i32 v[110:111], s[2:3], v109, s26, v[18:19]
	global_load_dwordx4 v[160:163], v[110:111], off
	v_add_u32_e32 v109, 8, v104
	v_mad_i64_i32 v[110:111], s[2:3], v109, s26, v[18:19]
	global_load_dwordx4 v[164:167], v[110:111], off
	v_add_u32_e32 v109, 16, v104
	v_mad_i64_i32 v[110:111], s[2:3], v109, s26, v[18:19]
	global_load_dwordx4 v[168:171], v[110:111], off
	v_add_u32_e32 v109, 24, v104
	v_mad_i64_i32 v[110:111], s[2:3], v109, s26, v[18:19]
	global_load_dwordx4 v[172:175], v[110:111], off
	v_add_u32_e32 v109, 32, v104
	v_mad_i64_i32 v[110:111], s[2:3], v109, s26, v[18:19]
	global_load_dwordx4 v[176:179], v[110:111], off
	v_add_u32_e32 v109, 40, v104
	v_mad_i64_i32 v[110:111], s[2:3], v109, s26, v[18:19]
	global_load_dwordx4 v[180:183], v[110:111], off
	v_add_u32_e32 v109, 48, v104
	v_mad_i64_i32 v[110:111], s[2:3], v109, s26, v[18:19]
	global_load_dwordx4 v[184:187], v[110:111], off
	v_add_u32_e32 v109, 56, v104
	v_mad_i64_i32 v[110:111], s[2:3], v109, s26, v[18:19]
	global_load_dwordx4 v[188:191], v[110:111], off
	s_waitcnt vmcnt(7)
	v_mul_f32_e32 v160, v160, v126
	ds_write_b32 v108, v160 offset:0
	v_mul_f32_e32 v161, v161, v126
	ds_write_b32 v108, v161 offset:4
	v_mul_f32_e32 v162, v162, v126
	ds_write_b32 v108, v162 offset:8
	v_mul_f32_e32 v163, v163, v126
	ds_write_b32 v108, v163 offset:12
	s_waitcnt vmcnt(6)
	v_mul_f32_e32 v164, v164, v127
	ds_write_b32 v108, v164 offset:1056
	v_mul_f32_e32 v165, v165, v127
	ds_write_b32 v108, v165 offset:1060
	v_mul_f32_e32 v166, v166, v127
	ds_write_b32 v108, v166 offset:1064
	v_mul_f32_e32 v167, v167, v127
	ds_write_b32 v108, v167 offset:1068
	s_waitcnt vmcnt(5)
	v_mul_f32_e32 v168, v168, v128
	ds_write_b32 v108, v168 offset:2112
	v_mul_f32_e32 v169, v169, v128
	ds_write_b32 v108, v169 offset:2116
	v_mul_f32_e32 v170, v170, v128
	ds_write_b32 v108, v170 offset:2120
	v_mul_f32_e32 v171, v171, v128
	ds_write_b32 v108, v171 offset:2124
	s_waitcnt vmcnt(4)
	v_mul_f32_e32 v172, v172, v129
	ds_write_b32 v108, v172 offset:3168
	v_mul_f32_e32 v173, v173, v129
	ds_write_b32 v108, v173 offset:3172
	v_mul_f32_e32 v174, v174, v129
	ds_write_b32 v108, v174 offset:3176
	v_mul_f32_e32 v175, v175, v129
	ds_write_b32 v108, v175 offset:3180
	s_waitcnt vmcnt(3)
	v_mul_f32_e32 v176, v176, v130
	ds_write_b32 v108, v176 offset:4224
	v_mul_f32_e32 v177, v177, v130
	ds_write_b32 v108, v177 offset:4228
	v_mul_f32_e32 v178, v178, v130
	ds_write_b32 v108, v178 offset:4232
	v_mul_f32_e32 v179, v179, v130
	ds_write_b32 v108, v179 offset:4236
	s_waitcnt vmcnt(2)
	v_mul_f32_e32 v180, v180, v131
	ds_write_b32 v108, v180 offset:5280
	v_mul_f32_e32 v181, v181, v131
	ds_write_b32 v108, v181 offset:5284
	v_mul_f32_e32 v182, v182, v131
	ds_write_b32 v108, v182 offset:5288
	v_mul_f32_e32 v183, v183, v131
	ds_write_b32 v108, v183 offset:5292
	s_waitcnt vmcnt(1)
	v_mul_f32_e32 v184, v184, v132
	ds_write_b32 v108, v184 offset:6336
	v_mul_f32_e32 v185, v185, v132
	ds_write_b32 v108, v185 offset:6340
	v_mul_f32_e32 v186, v186, v132
	ds_write_b32 v108, v186 offset:6344
	v_mul_f32_e32 v187, v187, v132
	ds_write_b32 v108, v187 offset:6348
	s_waitcnt vmcnt(0)
	v_mul_f32_e32 v188, v188, v133
	ds_write_b32 v108, v188 offset:7392
	v_mul_f32_e32 v189, v189, v133
	ds_write_b32 v108, v189 offset:7396
	v_mul_f32_e32 v190, v190, v133
	ds_write_b32 v108, v190 offset:7400
	v_mul_f32_e32 v191, v191, v133
	ds_write_b32 v108, v191 offset:7404
	ds_read_b32 v19, v93
	s_waitcnt lgkmcnt(0)
	s_branch .LBB0_54
